# GEMM main loop head aligned to 64 bytes (.p2align 6 before the loop label); code otherwise identical to the best version
# baseline (speedup 1.0000x reference)
; template <class EpiT>
; __device__ __forceinline__ void gemm_phase(LAS unsigned char* lds, const Gemm g, const StaticOrder& S, const EpiT& E, int wv) {
;     ...
;     { float z = 0.f; asm volatile("" : "+v"(z));
; #pragma unroll
;     for (int a = 0; a < 2; ++a)
; #pragma unroll
;         for (int b = 0; b < 2; ++b)
; #pragma unroll
;             for (int m = 0; m < 4; ++m)
; #pragma unroll
;                 for (int n = 0; n < 2; ++n) acc[a][b][m][n] = (f32x4){z, z, z, z}; }
.LBB0_270:
	s_add_u32 s0, s42, 0x80
	s_addc_u32 s1, s43, 0
	s_add_u32 s40, s40, 0x100
	v_mov_b64_e32 v[8:9], v[4:5]
	v_mov_b64_e32 v[24:25], v[4:5]
	v_mov_b64_e32 v[28:29], v[4:5]
	v_mov_b64_e32 v[40:41], v[4:5]
	v_mov_b64_e32 v[44:45], v[4:5]
	v_mov_b64_e32 v[56:57], v[4:5]
	v_mov_b64_e32 v[60:61], v[4:5]
	v_mov_b64_e32 v[12:13], v[4:5]
	v_mov_b64_e32 v[20:21], v[4:5]
	v_mov_b64_e32 v[32:33], v[4:5]
	v_mov_b64_e32 v[36:37], v[4:5]
	v_mov_b64_e32 v[48:49], v[4:5]
	v_mov_b64_e32 v[52:53], v[4:5]
	v_mov_b64_e32 v[64:65], v[4:5]
	v_mov_b64_e32 v[68:69], v[4:5]
	v_mov_b64_e32 v[72:73], v[4:5]
	v_mov_b64_e32 v[76:77], v[4:5]
	v_mov_b64_e32 v[88:89], v[4:5]
	v_mov_b64_e32 v[92:93], v[4:5]
	v_mov_b64_e32 v[104:105], v[4:5]
	v_mov_b64_e32 v[108:109], v[4:5]
	v_mov_b64_e32 v[120:121], v[4:5]
	v_mov_b64_e32 v[124:125], v[4:5]
	v_mov_b64_e32 v[80:81], v[4:5]
	v_mov_b64_e32 v[84:85], v[4:5]
	v_mov_b64_e32 v[96:97], v[4:5]
	v_mov_b64_e32 v[100:101], v[4:5]
	v_mov_b64_e32 v[112:113], v[4:5]
	v_mov_b64_e32 v[116:117], v[4:5]
	v_mov_b64_e32 v[128:129], v[4:5]
	v_mov_b64_e32 v[132:133], v[4:5]
	s_addc_u32 s41, s41, 0
	s_mov_b32 s22, 0
	v_mov_b64_e32 v[6:7], v[2:3]
	v_mov_b64_e32 v[22:23], v[2:3]
	v_mov_b64_e32 v[26:27], v[2:3]
	v_mov_b64_e32 v[38:39], v[2:3]
	v_mov_b64_e32 v[42:43], v[2:3]
	v_mov_b64_e32 v[54:55], v[2:3]
	v_mov_b64_e32 v[58:59], v[2:3]
	v_mov_b64_e32 v[10:11], v[2:3]
	v_mov_b64_e32 v[18:19], v[2:3]
	v_mov_b64_e32 v[30:31], v[2:3]
	v_mov_b64_e32 v[34:35], v[2:3]
	v_mov_b64_e32 v[46:47], v[2:3]
	v_mov_b64_e32 v[50:51], v[2:3]
	v_mov_b64_e32 v[62:63], v[2:3]
	v_mov_b64_e32 v[66:67], v[2:3]
	v_mov_b64_e32 v[70:71], v[2:3]
	v_mov_b64_e32 v[74:75], v[2:3]
	v_mov_b64_e32 v[86:87], v[2:3]
	v_mov_b64_e32 v[90:91], v[2:3]
	v_mov_b64_e32 v[102:103], v[2:3]
	v_mov_b64_e32 v[106:107], v[2:3]
	v_mov_b64_e32 v[118:119], v[2:3]
	v_mov_b64_e32 v[122:123], v[2:3]
	v_mov_b64_e32 v[78:79], v[2:3]
	v_mov_b64_e32 v[82:83], v[2:3]
	v_mov_b64_e32 v[94:95], v[2:3]
	v_mov_b64_e32 v[98:99], v[2:3]
	v_mov_b64_e32 v[110:111], v[2:3]
	v_mov_b64_e32 v[114:115], v[2:3]
	v_mov_b64_e32 v[126:127], v[2:3]
	v_mov_b64_e32 v[130:131], v[2:3]
	.p2align	6
